# adds: P0 round order rotated by 13 rounds for half of the workgroups (fourier-fold rounds overlap weight transposes of the other half)
# speedup vs baseline: 1.3803x; 1.0067x over previous
.LBB0_20:
	s_mov_b32 s100, s92
	s_bfe_u32 s101, s92, 0x10003
	s_cmp_eq_u32 s101, 0
	s_cbranch_scc1 .Lp0r_done
	s_and_b32 s101, s92, 0xff
	s_lshr_b32 s100, s92, 8
	s_add_i32 s100, s100, 13
	s_cmpk_lt_u32 s101, 0x4d
	s_cselect_b32 s0, 18, 17
	s_cmp_lt_u32 s100, s0
	s_cbranch_scc1 .Lp0r_nowrap
	s_sub_u32 s100, s100, s0
.Lp0r_nowrap:
	s_lshl_b32 s100, s100, 8
	s_or_b32 s100, s100, s101
.Lp0r_done:
	s_lshl_b32 s101, s100, 1
	s_add_i32 s101, s101, 0xffffe57e
	v_mov_b32_e32 v0, v200
	s_movk_i32 s0, 0x17f
	v_ashrrev_i32_e32 v0, 8, v0
	v_lshl_add_u32 v4, s100, 1, v0
	v_cmp_lt_i32_e32 vcc, s0, v4
	s_and_saveexec_b64 s[0:1], vcc
	s_xor_b64 s[68:69], exec, s[0:1]
	s_cbranch_execz .LBB0_104
	s_movk_i32 s0, 0xc7f
	v_cmp_lt_u32_e32 vcc, s0, v4
	s_and_saveexec_b64 s[0:1], vcc
	s_xor_b64 s[70:71], exec, s[0:1]
	s_cbranch_execz .LBB0_101
	s_movk_i32 s0, 0x107f
	v_cmp_lt_u32_e32 vcc, s0, v4
	s_and_saveexec_b64 s[0:1], vcc
	s_xor_b64 s[72:73], exec, s[0:1]
	s_cbranch_execz .LBB0_98
	s_movk_i32 s0, 0x10bf
	v_cmp_lt_u32_e32 vcc, s0, v4
	s_and_saveexec_b64 s[0:1], vcc
	s_xor_b64 s[74:75], exec, s[0:1]
	s_cbranch_execz .LBB0_95
	s_movk_i32 s0, 0x113f
	v_cmp_lt_u32_e32 vcc, s0, v4
	s_and_saveexec_b64 s[0:1], vcc
	s_xor_b64 s[76:77], exec, s[0:1]
	s_cbranch_execz .LBB0_90
	s_movk_i32 s0, 0x123f
	v_cmp_lt_u32_e32 vcc, s0, v4
	s_and_saveexec_b64 s[0:1], vcc
	s_xor_b64 s[78:79], exec, s[0:1]
	s_cbranch_execz .LBB0_87
	s_movk_i32 s0, 0x163f
	v_cmp_lt_u32_e32 vcc, s0, v4
	s_and_saveexec_b64 s[0:1], vcc
	s_xor_b64 s[80:81], exec, s[0:1]
	s_cbranch_execz .LBB0_84
	s_movk_i32 s0, 0x1a7f
	v_cmp_lt_u32_e32 vcc, s0, v4
	s_and_saveexec_b64 s[0:1], vcc
	s_xor_b64 s[0:1], exec, s[0:1]
	s_cbranch_execz .LBB0_81
	s_movk_i32 s82, 0x1a81
	v_cmp_lt_u32_e32 vcc, s82, v4
	s_and_saveexec_b64 s[82:83], vcc
	s_xor_b64 s[82:83], exec, s[82:83]
	s_cbranch_execz .LBB0_78
	v_writelane_b32 v254, s82, 1
	s_nop 1
	v_writelane_b32 v254, s83, 2
	s_movk_i32 s82, 0x2281
	v_cmp_lt_u32_e32 vcc, s82, v4
	s_and_saveexec_b64 s[82:83], vcc
	s_xor_b64 s[82:83], exec, s[82:83]
	v_writelane_b32 v254, s82, 3
	s_nop 1
	v_writelane_b32 v254, s83, 4
	s_cbranch_execz .LBB0_71
	v_add_u32_e32 v0, 0xffffdd7a, v4
	v_cmp_lt_u32_e32 vcc, 15, v0
	s_and_saveexec_b64 s[82:83], vcc
	s_xor_b64 s[82:83], exec, s[82:83]
	s_cbranch_execz .LBB0_60
	v_writelane_b32 v254, s82, 5
	s_nop 1
	v_writelane_b32 v254, s83, 6
	s_movk_i32 s82, 0x2284
	v_cmp_lt_i32_e32 vcc, s82, v4
	s_and_saveexec_b64 s[82:83], vcc
	s_xor_b64 s[82:83], exec, s[82:83]
	v_writelane_b32 v254, s82, 7
	s_nop 1
	v_writelane_b32 v254, s83, 8
	s_cbranch_execz .LBB0_51
	s_movk_i32 s82, 0x2296
	v_cmp_lt_i32_e32 vcc, s82, v4
	s_mov_b64 s[86:87], 0
	s_and_saveexec_b64 s[82:83], vcc
	s_xor_b64 s[82:83], exec, s[82:83]
	v_writelane_b32 v254, s82, 9
	s_nop 1
	v_writelane_b32 v254, s83, 10
	s_cbranch_execz .LBB0_40
	s_movk_i32 s82, 0x2297
	v_cmp_lt_i32_e32 vcc, s82, v4
	s_mov_b64 s[82:83], 0
	v_mov_b64_e32 v[0:1], s[10:11]
	s_and_saveexec_b64 s[86:87], vcc
	s_xor_b64 s[86:87], exec, s[86:87]
	s_cbranch_execz .LBB0_37
	s_movk_i32 s82, 0x2298
	v_cmp_eq_u32_e32 vcc, s82, v4
	s_mov_b64 s[82:83], -1
	v_writelane_b32 v254, s82, 11
	s_nop 1
	v_writelane_b32 v254, s83, 12
	s_and_saveexec_b64 s[82:83], vcc
	s_cbranch_execz .LBB0_36
	s_xor_b64 vcc, exec, -1
	v_writelane_b32 v254, vcc_lo, 11
	s_nop 1
	v_writelane_b32 v254, vcc_hi, 12

.LBB0_74:
	s_or_b64 exec, exec, s[86:87]
	v_add_u32_e32 v4, 0xffffe57e, v4
	v_lshlrev_b32_e32 v2, 8, v4
	v_and_or_b32 v6, v2, s94, v1
	v_add_u32_e32 v2, s101, v0
	v_lshlrev_b32_e32 v0, 8, v2
	s_mov_b32 s86, 0x70000
	v_and_or_b32 v0, v0, s86, v6
	v_lshlrev_b32_e32 v76, 2, v0
	v_lshrrev_b32_e32 v7, 1, v2
	v_and_b32_e32 v9, -2, v2
	v_mov_b32_e32 v2, 0
	v_lshl_add_u64 v[0:1], s[56:57], 0, v[76:77]
	v_lshlrev_b32_e32 v8, 4, v7
	v_lshl_add_u32 v10, v7, 1, v7
	v_lshlrev_b32_e32 v11, 2, v7
	v_lshl_add_u32 v12, v7, 2, v7
	v_mul_lo_u32 v13, v7, 6
	v_mul_lo_u32 v14, v7, 7
	v_lshlrev_b32_e32 v15, 3, v7
	v_lshl_add_u32 v16, v7, 3, v7
	v_mul_lo_u32 v17, v7, 10
	v_mul_lo_u32 v18, v7, 11
	v_mul_lo_u32 v19, v7, 12
	v_mul_lo_u32 v20, v7, 13
	v_mul_lo_u32 v21, v7, 14
	v_mul_lo_u32 v22, v7, 15
	s_mov_b64 s[86:87], 0
	v_mov_b32_e32 v23, 0
	v_mov_b32_e32 v3, v2
	s_waitcnt lgkmcnt(0)
	s_barrier
